# GEMM K-loops: matrix-segment end barrier signalled 4 MFMAs early (was 2)
# speedup vs baseline: 1.0029x; 1.0029x over previous
.LBB0_126:
	ds_read_b128 v[148:151], v159
	ds_read_b128 v[152:155], v159 offset:1024
	ds_read_b128 v[162:165], v159 offset:2048
	ds_read_b128 v[166:169], v159 offset:3072
	ds_read_b128 v[170:173], v160
	ds_read_b128 v[174:177], v160 offset:1024
	ds_read_b128 v[178:181], v160 offset:2048
	ds_read_b128 v[182:185], v160 offset:3072
	s_add_u32 s34, s30, 0xfffc0080
	s_addc_u32 s35, s31, -1
	s_cmp_eq_u32 s72, 12
	s_cselect_b32 s37, s5, s35
	s_cselect_b32 s36, s38, s34
	s_cselect_b32 s35, s39, s71
	s_cselect_b32 s34, s44, s45
	v_lshl_add_u64 v[156:157], s[30:31], 0, v[140:141]
	s_add_i32 m0, s48, 0xc000
	ds_read_b128 v[186:189], v161
	ds_read_b128 v[190:193], v161 offset:1024
	ds_read_b128 v[194:197], v161 offset:2048
	ds_read_b128 v[198:201], v161 offset:3072
	ds_read_b128 v[202:205], v161 offset:4096
	ds_read_b128 v[206:209], v161 offset:5120
	ds_read_b128 v[210:213], v161 offset:6144
	ds_read_b128 v[214:217], v161 offset:7168
	global_load_lds_dwordx4 v[156:157], off
	v_lshl_add_u64 v[156:157], s[30:31], 0, v[142:143]
	s_add_i32 m0, s48, 0xe000
	s_nop 0
	global_load_lds_dwordx4 v[156:157], off
	s_waitcnt vmcnt(8)
	s_waitcnt lgkmcnt(0)
	s_barrier
	s_setprio 1
	s_waitcnt lgkmcnt(0)
	v_mfma_f32_16x16x32_bf16 v[126:129], v[148:151], v[186:189], v[126:129]
	v_mfma_f32_16x16x32_bf16 v[122:125], v[162:165], v[186:189], v[122:125]
	v_mfma_f32_16x16x32_bf16 v[110:113], v[148:151], v[194:197], v[110:113]
	v_mfma_f32_16x16x32_bf16 v[106:109], v[162:165], v[194:197], v[106:109]
	v_mfma_f32_16x16x32_bf16 v[94:97], v[148:151], v[202:205], v[94:97]
	v_mfma_f32_16x16x32_bf16 v[90:93], v[162:165], v[202:205], v[90:93]
	v_mfma_f32_16x16x32_bf16 v[78:81], v[148:151], v[210:213], v[78:81]
	v_mfma_f32_16x16x32_bf16 v[74:77], v[162:165], v[210:213], v[74:77]
	v_mfma_f32_16x16x32_bf16 v[126:129], v[152:155], v[190:193], v[126:129]
	v_mfma_f32_16x16x32_bf16 v[122:125], v[166:169], v[190:193], v[122:125]
	v_mfma_f32_16x16x32_bf16 v[110:113], v[152:155], v[198:201], v[110:113]
	v_mfma_f32_16x16x32_bf16 v[106:109], v[166:169], v[198:201], v[106:109]
	v_mfma_f32_16x16x32_bf16 v[94:97], v[152:155], v[206:209], v[94:97]
	v_mfma_f32_16x16x32_bf16 v[90:93], v[166:169], v[206:209], v[90:93]
	v_mfma_f32_16x16x32_bf16 v[78:81], v[152:155], v[214:217], v[78:81]
	v_mfma_f32_16x16x32_bf16 v[74:77], v[166:169], v[214:217], v[74:77]
	s_setprio 0
	s_setprio 1
	v_mfma_f32_16x16x32_bf16 v[118:121], v[170:173], v[186:189], v[118:121]
	v_mfma_f32_16x16x32_bf16 v[114:117], v[178:181], v[186:189], v[114:117]
	v_mfma_f32_16x16x32_bf16 v[102:105], v[170:173], v[194:197], v[102:105]
	v_mfma_f32_16x16x32_bf16 v[98:101], v[178:181], v[194:197], v[98:101]
	v_mfma_f32_16x16x32_bf16 v[86:89], v[170:173], v[202:205], v[86:89]
	v_mfma_f32_16x16x32_bf16 v[82:85], v[178:181], v[202:205], v[82:85]
	v_mfma_f32_16x16x32_bf16 v[70:73], v[170:173], v[210:213], v[70:73]
	v_mfma_f32_16x16x32_bf16 v[66:69], v[178:181], v[210:213], v[66:69]
	v_mfma_f32_16x16x32_bf16 v[118:121], v[174:177], v[190:193], v[118:121]
	v_mfma_f32_16x16x32_bf16 v[114:117], v[182:185], v[190:193], v[114:117]
	v_mfma_f32_16x16x32_bf16 v[102:105], v[174:177], v[198:201], v[102:105]
	v_mfma_f32_16x16x32_bf16 v[98:101], v[182:185], v[198:201], v[98:101]
	s_setprio 2
	s_barrier
	v_mfma_f32_16x16x32_bf16 v[86:89], v[174:177], v[206:209], v[86:89]
	v_mfma_f32_16x16x32_bf16 v[82:85], v[182:185], v[206:209], v[82:85]
	v_mfma_f32_16x16x32_bf16 v[70:73], v[174:177], v[214:217], v[70:73]
	v_mfma_f32_16x16x32_bf16 v[66:69], v[182:185], v[214:217], v[66:69]
	s_setprio 0
	s_add_i32 s73, s65, s47
	v_lshl_add_u64 v[156:157], s[34:35], 0, v[132:133]
	s_mov_b32 m0, s73
	ds_read_b128 v[186:189], v161 offset:16384
	ds_read_b128 v[190:193], v161 offset:17408
	ds_read_b128 v[194:197], v161 offset:18432
	ds_read_b128 v[198:201], v161 offset:19456
	ds_read_b128 v[202:205], v161 offset:20480
	ds_read_b128 v[206:209], v161 offset:21504
	ds_read_b128 v[210:213], v161 offset:22528
	ds_read_b128 v[214:217], v161 offset:23552
	global_load_lds_dwordx4 v[156:157], off
	s_add_i32 m0, s73, 0x2000
	s_add_u32 s74, s34, 0x40000
	v_lshl_add_u64 v[218:219], s[34:35], 0, v[136:137]
	s_addc_u32 s75, s35, 0
	s_add_i32 s73, s66, s47
	global_load_lds_dwordx4 v[218:219], off
	v_lshl_add_u64 v[220:221], s[74:75], 0, v[132:133]
	s_mov_b32 m0, s73
	v_lshl_add_u64 v[222:223], s[36:37], 0, v[134:135]
	global_load_lds_dwordx4 v[220:221], off
	v_lshl_add_u64 v[220:221], s[74:75], 0, v[136:137]
	s_add_i32 m0, s73, 0x2000
	s_nop 0
	global_load_lds_dwordx4 v[220:221], off
	v_lshl_add_u64 v[220:221], s[36:37], 0, v[130:131]
	s_mov_b32 m0, s48
	s_nop 0
	global_load_lds_dwordx4 v[220:221], off
	s_mov_b32 m0, s49
	s_nop 0
	global_load_lds_dwordx4 v[222:223], off
	s_waitcnt vmcnt(8)
	s_waitcnt lgkmcnt(0)
	s_barrier
	s_setprio 1
	s_waitcnt lgkmcnt(0)
	v_mfma_f32_16x16x32_bf16 v[62:65], v[148:151], v[186:189], v[62:65]
	v_mfma_f32_16x16x32_bf16 v[58:61], v[162:165], v[186:189], v[58:61]
	v_mfma_f32_16x16x32_bf16 v[46:49], v[148:151], v[194:197], v[46:49]
	v_mfma_f32_16x16x32_bf16 v[42:45], v[162:165], v[194:197], v[42:45]
	v_mfma_f32_16x16x32_bf16 v[30:33], v[148:151], v[202:205], v[30:33]
	v_mfma_f32_16x16x32_bf16 v[26:29], v[162:165], v[202:205], v[26:29]
	v_mfma_f32_16x16x32_bf16 v[14:17], v[148:151], v[210:213], v[14:17]
	v_mfma_f32_16x16x32_bf16 v[10:13], v[162:165], v[210:213], v[10:13]
	v_mfma_f32_16x16x32_bf16 v[62:65], v[152:155], v[190:193], v[62:65]
	v_mfma_f32_16x16x32_bf16 v[58:61], v[166:169], v[190:193], v[58:61]
	v_mfma_f32_16x16x32_bf16 v[46:49], v[152:155], v[198:201], v[46:49]
	v_mfma_f32_16x16x32_bf16 v[42:45], v[166:169], v[198:201], v[42:45]
	v_mfma_f32_16x16x32_bf16 v[30:33], v[152:155], v[206:209], v[30:33]
	v_mfma_f32_16x16x32_bf16 v[26:29], v[166:169], v[206:209], v[26:29]
	v_mfma_f32_16x16x32_bf16 v[14:17], v[152:155], v[214:217], v[14:17]
	v_mfma_f32_16x16x32_bf16 v[10:13], v[166:169], v[214:217], v[10:13]
	s_setprio 0
	s_setprio 1
	v_mfma_f32_16x16x32_bf16 v[54:57], v[170:173], v[186:189], v[54:57]
	v_mfma_f32_16x16x32_bf16 v[50:53], v[178:181], v[186:189], v[50:53]
	v_mfma_f32_16x16x32_bf16 v[38:41], v[170:173], v[194:197], v[38:41]
	v_mfma_f32_16x16x32_bf16 v[34:37], v[178:181], v[194:197], v[34:37]
	v_mfma_f32_16x16x32_bf16 v[22:25], v[170:173], v[202:205], v[22:25]
	v_mfma_f32_16x16x32_bf16 v[18:21], v[178:181], v[202:205], v[18:21]
	v_mfma_f32_16x16x32_bf16 v[6:9], v[170:173], v[210:213], v[6:9]
	v_mfma_f32_16x16x32_bf16 v[2:5], v[178:181], v[210:213], v[2:5]
	v_mfma_f32_16x16x32_bf16 v[54:57], v[174:177], v[190:193], v[54:57]
	v_mfma_f32_16x16x32_bf16 v[50:53], v[182:185], v[190:193], v[50:53]
	v_mfma_f32_16x16x32_bf16 v[38:41], v[174:177], v[198:201], v[38:41]
	v_mfma_f32_16x16x32_bf16 v[34:37], v[182:185], v[198:201], v[34:37]
	s_setprio 2
	s_barrier
	v_mfma_f32_16x16x32_bf16 v[22:25], v[174:177], v[206:209], v[22:25]
	v_mfma_f32_16x16x32_bf16 v[18:21], v[182:185], v[206:209], v[18:21]
	v_mfma_f32_16x16x32_bf16 v[6:9], v[174:177], v[214:217], v[6:9]
	v_mfma_f32_16x16x32_bf16 v[2:5], v[182:185], v[214:217], v[2:5]
	s_setprio 0
	s_add_i32 s73, 0, 0x18000
	v_add_u32_e32 v138, s73, v158
	s_add_i32 s74, 0, 0x1c000
	ds_read_b128 v[148:151], v138
	ds_read_b128 v[152:155], v138 offset:1024
	ds_read_b128 v[162:165], v138 offset:2048
	ds_read_b128 v[166:169], v138 offset:3072
	v_add_u32_e32 v138, s74, v158
	ds_read_b128 v[170:173], v138
	ds_read_b128 v[174:177], v138 offset:1024
	ds_read_b128 v[178:181], v138 offset:2048
	ds_read_b128 v[182:185], v138 offset:3072
	s_add_u32 s36, s36, 0x40000
	s_addc_u32 s37, s37, 0
	s_mov_b32 m0, s50
	v_lshl_add_u64 v[224:225], s[36:37], 0, v[130:131]
	ds_read_b128 v[186:189], v161 offset:32768
	ds_read_b128 v[190:193], v161 offset:33792
	ds_read_b128 v[194:197], v161 offset:34816
	ds_read_b128 v[198:201], v161 offset:35840
	ds_read_b128 v[202:205], v161 offset:36864
	ds_read_b128 v[206:209], v161 offset:37888
	ds_read_b128 v[210:213], v161 offset:38912
	ds_read_b128 v[214:217], v161 offset:39936
	global_load_lds_dwordx4 v[224:225], off
	v_lshl_add_u64 v[224:225], s[36:37], 0, v[134:135]
	s_mov_b32 m0, s51
	s_nop 0
	global_load_lds_dwordx4 v[224:225], off
	s_waitcnt vmcnt(8)
	s_waitcnt lgkmcnt(0)
	s_barrier
	s_setprio 1
	s_waitcnt lgkmcnt(0)
	v_mfma_f32_16x16x32_bf16 v[126:129], v[148:151], v[186:189], v[126:129]
	v_mfma_f32_16x16x32_bf16 v[122:125], v[162:165], v[186:189], v[122:125]
	v_mfma_f32_16x16x32_bf16 v[110:113], v[148:151], v[194:197], v[110:113]
	v_mfma_f32_16x16x32_bf16 v[106:109], v[162:165], v[194:197], v[106:109]
	v_mfma_f32_16x16x32_bf16 v[94:97], v[148:151], v[202:205], v[94:97]
	v_mfma_f32_16x16x32_bf16 v[90:93], v[162:165], v[202:205], v[90:93]
	v_mfma_f32_16x16x32_bf16 v[78:81], v[148:151], v[210:213], v[78:81]
	v_mfma_f32_16x16x32_bf16 v[74:77], v[162:165], v[210:213], v[74:77]
	v_mfma_f32_16x16x32_bf16 v[126:129], v[152:155], v[190:193], v[126:129]
	v_mfma_f32_16x16x32_bf16 v[122:125], v[166:169], v[190:193], v[122:125]
	v_mfma_f32_16x16x32_bf16 v[110:113], v[152:155], v[198:201], v[110:113]
	v_mfma_f32_16x16x32_bf16 v[106:109], v[166:169], v[198:201], v[106:109]
	v_mfma_f32_16x16x32_bf16 v[94:97], v[152:155], v[206:209], v[94:97]
	v_mfma_f32_16x16x32_bf16 v[90:93], v[166:169], v[206:209], v[90:93]
	v_mfma_f32_16x16x32_bf16 v[78:81], v[152:155], v[214:217], v[78:81]
	v_mfma_f32_16x16x32_bf16 v[74:77], v[166:169], v[214:217], v[74:77]
	s_setprio 0
	s_setprio 1
	v_mfma_f32_16x16x32_bf16 v[118:121], v[170:173], v[186:189], v[118:121]
	v_mfma_f32_16x16x32_bf16 v[114:117], v[178:181], v[186:189], v[114:117]
	v_mfma_f32_16x16x32_bf16 v[102:105], v[170:173], v[194:197], v[102:105]
	v_mfma_f32_16x16x32_bf16 v[98:101], v[178:181], v[194:197], v[98:101]
	v_mfma_f32_16x16x32_bf16 v[86:89], v[170:173], v[202:205], v[86:89]
	v_mfma_f32_16x16x32_bf16 v[82:85], v[178:181], v[202:205], v[82:85]
	v_mfma_f32_16x16x32_bf16 v[70:73], v[170:173], v[210:213], v[70:73]
	v_mfma_f32_16x16x32_bf16 v[66:69], v[178:181], v[210:213], v[66:69]
	v_mfma_f32_16x16x32_bf16 v[118:121], v[174:177], v[190:193], v[118:121]
	v_mfma_f32_16x16x32_bf16 v[114:117], v[182:185], v[190:193], v[114:117]
	v_mfma_f32_16x16x32_bf16 v[102:105], v[174:177], v[198:201], v[102:105]
	v_mfma_f32_16x16x32_bf16 v[98:101], v[182:185], v[198:201], v[98:101]
	s_setprio 2
	s_barrier
	v_mfma_f32_16x16x32_bf16 v[86:89], v[174:177], v[206:209], v[86:89]
	v_mfma_f32_16x16x32_bf16 v[82:85], v[182:185], v[206:209], v[82:85]
	v_mfma_f32_16x16x32_bf16 v[70:73], v[174:177], v[214:217], v[70:73]
	v_mfma_f32_16x16x32_bf16 v[66:69], v[182:185], v[214:217], v[66:69]
	s_setprio 0
	s_add_i32 s36, s73, s47
	v_lshl_add_u64 v[156:157], v[156:157], 0, s[14:15]
	s_mov_b32 m0, s36
	ds_read_b128 v[186:189], v161 offset:49152
	ds_read_b128 v[190:193], v161 offset:50176
	ds_read_b128 v[194:197], v161 offset:51200
	ds_read_b128 v[198:201], v161 offset:52224
	ds_read_b128 v[202:205], v161 offset:53248
	ds_read_b128 v[206:209], v161 offset:54272
	ds_read_b128 v[210:213], v161 offset:55296
	ds_read_b128 v[214:217], v161 offset:56320
	global_load_lds_dwordx4 v[156:157], off
	s_add_i32 m0, s36, 0x2000
	s_add_u32 s34, s34, 0x40080
	v_lshl_add_u64 v[156:157], v[218:219], 0, s[14:15]
	s_addc_u32 s35, s35, 0
	s_add_i32 s36, s74, s47
	global_load_lds_dwordx4 v[156:157], off
	v_lshl_add_u64 v[156:157], s[34:35], 0, v[132:133]
	s_mov_b32 m0, s36
	s_nop 0
	global_load_lds_dwordx4 v[156:157], off
	v_lshl_add_u64 v[156:157], s[34:35], 0, v[136:137]
	s_add_i32 m0, s36, 0x2000
	s_nop 0
	global_load_lds_dwordx4 v[156:157], off
	v_lshl_add_u64 v[156:157], v[220:221], 0, s[14:15]
	s_mov_b32 m0, s62
	s_nop 0
	global_load_lds_dwordx4 v[156:157], off
	v_lshl_add_u64 v[156:157], v[222:223], 0, s[14:15]
	s_mov_b32 m0, s63
	s_nop 0
	global_load_lds_dwordx4 v[156:157], off
	s_waitcnt vmcnt(8)
	s_waitcnt lgkmcnt(0)
	s_barrier
	s_setprio 1
	s_waitcnt lgkmcnt(0)
	v_mfma_f32_16x16x32_bf16 v[62:65], v[148:151], v[186:189], v[62:65]
	v_mfma_f32_16x16x32_bf16 v[58:61], v[162:165], v[186:189], v[58:61]
	v_mfma_f32_16x16x32_bf16 v[46:49], v[148:151], v[194:197], v[46:49]
	v_mfma_f32_16x16x32_bf16 v[42:45], v[162:165], v[194:197], v[42:45]
	v_mfma_f32_16x16x32_bf16 v[30:33], v[148:151], v[202:205], v[30:33]
	v_mfma_f32_16x16x32_bf16 v[26:29], v[162:165], v[202:205], v[26:29]
	v_mfma_f32_16x16x32_bf16 v[14:17], v[148:151], v[210:213], v[14:17]
	v_mfma_f32_16x16x32_bf16 v[10:13], v[162:165], v[210:213], v[10:13]
	v_mfma_f32_16x16x32_bf16 v[62:65], v[152:155], v[190:193], v[62:65]
	v_mfma_f32_16x16x32_bf16 v[58:61], v[166:169], v[190:193], v[58:61]
	v_mfma_f32_16x16x32_bf16 v[46:49], v[152:155], v[198:201], v[46:49]
	v_mfma_f32_16x16x32_bf16 v[42:45], v[166:169], v[198:201], v[42:45]
	v_mfma_f32_16x16x32_bf16 v[30:33], v[152:155], v[206:209], v[30:33]
	v_mfma_f32_16x16x32_bf16 v[26:29], v[166:169], v[206:209], v[26:29]
	v_mfma_f32_16x16x32_bf16 v[14:17], v[152:155], v[214:217], v[14:17]
	v_mfma_f32_16x16x32_bf16 v[10:13], v[166:169], v[214:217], v[10:13]
	s_setprio 0
	s_setprio 1
	v_mfma_f32_16x16x32_bf16 v[54:57], v[170:173], v[186:189], v[54:57]
	v_mfma_f32_16x16x32_bf16 v[50:53], v[178:181], v[186:189], v[50:53]
	v_mfma_f32_16x16x32_bf16 v[38:41], v[170:173], v[194:197], v[38:41]
	v_mfma_f32_16x16x32_bf16 v[34:37], v[178:181], v[194:197], v[34:37]
	v_mfma_f32_16x16x32_bf16 v[22:25], v[170:173], v[202:205], v[22:25]
	v_mfma_f32_16x16x32_bf16 v[18:21], v[178:181], v[202:205], v[18:21]
	v_mfma_f32_16x16x32_bf16 v[6:9], v[170:173], v[210:213], v[6:9]
	v_mfma_f32_16x16x32_bf16 v[2:5], v[178:181], v[210:213], v[2:5]
	v_mfma_f32_16x16x32_bf16 v[54:57], v[174:177], v[190:193], v[54:57]
	v_mfma_f32_16x16x32_bf16 v[50:53], v[182:185], v[190:193], v[50:53]
	v_mfma_f32_16x16x32_bf16 v[38:41], v[174:177], v[198:201], v[38:41]
	v_mfma_f32_16x16x32_bf16 v[34:37], v[182:185], v[198:201], v[34:37]
	s_setprio 2
	s_barrier
	v_mfma_f32_16x16x32_bf16 v[22:25], v[174:177], v[206:209], v[22:25]
	v_mfma_f32_16x16x32_bf16 v[18:21], v[182:185], v[206:209], v[18:21]
	v_mfma_f32_16x16x32_bf16 v[6:9], v[174:177], v[214:217], v[6:9]
	v_mfma_f32_16x16x32_bf16 v[2:5], v[182:185], v[214:217], v[2:5]
	s_setprio 0
	s_add_i32 s72, s72, 2
	s_add_u32 s30, s30, 0x100
	s_addc_u32 s31, s31, 0
	s_add_u32 s45, s45, 0x100
	s_addc_u32 s71, s71, 0
	s_cmp_gt_u32 s72, 13
	s_cbranch_scc0 .LBB0_126
	s_and_b64 vcc, exec, s[18:19]
	s_cbranch_vccz .LBB0_129
	s_barrier

.LBB0_761:
	v_add_u32_e32 v164, s62, v150
	v_add_u32_e32 v180, s63, v150
	s_add_u32 s34, s16, s26
	ds_read_b128 v[152:155], v164
	ds_read_b128 v[156:159], v164 offset:1024
	ds_read_b128 v[160:163], v164 offset:2048
	ds_read_b128 v[164:167], v164 offset:3072
	ds_read_b128 v[168:171], v180
	ds_read_b128 v[172:175], v180 offset:1024
	ds_read_b128 v[176:179], v180 offset:2048
	ds_read_b128 v[180:183], v180 offset:3072
	s_addc_u32 s35, s17, s27
	s_add_u32 s34, s34, 0x100
	s_addc_u32 s35, s35, 0
	s_add_u32 s68, s21, s26
	s_addc_u32 s69, s66, s27
	s_cmpk_eq_i32 s26, 0xf00
	s_cselect_b32 s37, s29, s35
	s_cselect_b32 s36, s28, s34
	s_cselect_b32 s35, s31, s69
	s_cselect_b32 s34, s30, s68
	v_lshl_add_u64 v[216:217], v[146:147], 0, s[26:27]
	s_add_i32 m0, s15, 0xc000
	ds_read_b128 v[184:187], v151
	ds_read_b128 v[188:191], v151 offset:1024
	ds_read_b128 v[192:195], v151 offset:2048
	ds_read_b128 v[196:199], v151 offset:3072
	ds_read_b128 v[200:203], v151 offset:4096
	ds_read_b128 v[204:207], v151 offset:5120
	ds_read_b128 v[208:211], v151 offset:6144
	ds_read_b128 v[212:215], v151 offset:7168
	global_load_lds_dwordx4 v[216:217], off
	v_lshl_add_u64 v[216:217], v[148:149], 0, s[26:27]
	s_add_i32 m0, s15, 0xe000
	s_nop 0
	global_load_lds_dwordx4 v[216:217], off
	s_waitcnt vmcnt(8)
	s_waitcnt lgkmcnt(0)
	s_barrier
	s_setprio 1
	s_waitcnt lgkmcnt(0)
	v_mfma_f32_16x16x32_bf16 v[126:129], v[152:155], v[184:187], v[126:129]
	v_mfma_f32_16x16x32_bf16 v[122:125], v[160:163], v[184:187], v[122:125]
	v_mfma_f32_16x16x32_bf16 v[118:121], v[152:155], v[192:195], v[118:121]
	v_mfma_f32_16x16x32_bf16 v[114:117], v[160:163], v[192:195], v[114:117]
	v_mfma_f32_16x16x32_bf16 v[94:97], v[152:155], v[200:203], v[94:97]
	v_mfma_f32_16x16x32_bf16 v[90:93], v[160:163], v[200:203], v[90:93]
	v_mfma_f32_16x16x32_bf16 v[86:89], v[152:155], v[208:211], v[86:89]
	v_mfma_f32_16x16x32_bf16 v[82:85], v[160:163], v[208:211], v[82:85]
	v_mfma_f32_16x16x32_bf16 v[126:129], v[156:159], v[188:191], v[126:129]
	v_mfma_f32_16x16x32_bf16 v[122:125], v[164:167], v[188:191], v[122:125]
	v_mfma_f32_16x16x32_bf16 v[118:121], v[156:159], v[196:199], v[118:121]
	v_mfma_f32_16x16x32_bf16 v[114:117], v[164:167], v[196:199], v[114:117]
	v_mfma_f32_16x16x32_bf16 v[94:97], v[156:159], v[204:207], v[94:97]
	v_mfma_f32_16x16x32_bf16 v[90:93], v[164:167], v[204:207], v[90:93]
	v_mfma_f32_16x16x32_bf16 v[86:89], v[156:159], v[212:215], v[86:89]
	v_mfma_f32_16x16x32_bf16 v[82:85], v[164:167], v[212:215], v[82:85]
	s_setprio 0
	s_setprio 1
	v_mfma_f32_16x16x32_bf16 v[110:113], v[168:171], v[184:187], v[110:113]
	v_mfma_f32_16x16x32_bf16 v[106:109], v[176:179], v[184:187], v[106:109]
	v_mfma_f32_16x16x32_bf16 v[102:105], v[168:171], v[192:195], v[102:105]
	v_mfma_f32_16x16x32_bf16 v[98:101], v[176:179], v[192:195], v[98:101]
	v_mfma_f32_16x16x32_bf16 v[78:81], v[168:171], v[200:203], v[78:81]
	v_mfma_f32_16x16x32_bf16 v[74:77], v[176:179], v[200:203], v[74:77]
	v_mfma_f32_16x16x32_bf16 v[70:73], v[168:171], v[208:211], v[70:73]
	v_mfma_f32_16x16x32_bf16 v[66:69], v[176:179], v[208:211], v[66:69]
	v_mfma_f32_16x16x32_bf16 v[110:113], v[172:175], v[188:191], v[110:113]
	v_mfma_f32_16x16x32_bf16 v[106:109], v[180:183], v[188:191], v[106:109]
	v_mfma_f32_16x16x32_bf16 v[102:105], v[172:175], v[196:199], v[102:105]
	v_mfma_f32_16x16x32_bf16 v[98:101], v[180:183], v[196:199], v[98:101]
	s_setprio 2
	s_barrier
	v_mfma_f32_16x16x32_bf16 v[78:81], v[172:175], v[204:207], v[78:81]
	v_mfma_f32_16x16x32_bf16 v[74:77], v[180:183], v[204:207], v[74:77]
	v_mfma_f32_16x16x32_bf16 v[70:73], v[172:175], v[212:215], v[70:73]
	v_mfma_f32_16x16x32_bf16 v[66:69], v[180:183], v[212:215], v[66:69]
	s_setprio 0
	s_add_i32 s68, s62, s48
	v_lshl_add_u64 v[216:217], s[34:35], 0, v[132:133]
	s_mov_b32 m0, s68
	ds_read_b128 v[184:187], v151 offset:16384
	ds_read_b128 v[188:191], v151 offset:17408
	ds_read_b128 v[192:195], v151 offset:18432
	ds_read_b128 v[196:199], v151 offset:19456
	ds_read_b128 v[200:203], v151 offset:20480
	ds_read_b128 v[204:207], v151 offset:21504
	ds_read_b128 v[208:211], v151 offset:22528
	ds_read_b128 v[212:215], v151 offset:23552
	global_load_lds_dwordx4 v[216:217], off
	s_add_i32 m0, s68, 0x2000
	s_add_u32 s68, s34, 0x80000
	v_lshl_add_u64 v[218:219], s[34:35], 0, v[136:137]
	s_addc_u32 s69, s35, 0
	s_add_i32 s70, s63, s48
	global_load_lds_dwordx4 v[218:219], off
	v_lshl_add_u64 v[220:221], s[68:69], 0, v[132:133]
	s_mov_b32 m0, s70
	v_lshl_add_u64 v[222:223], s[36:37], 0, v[134:135]
	global_load_lds_dwordx4 v[220:221], off
	v_lshl_add_u64 v[220:221], s[68:69], 0, v[136:137]
	s_add_i32 m0, s70, 0x2000
	s_nop 0
	global_load_lds_dwordx4 v[220:221], off
	v_lshl_add_u64 v[220:221], s[36:37], 0, v[130:131]
	s_mov_b32 m0, s15
	s_nop 0
	global_load_lds_dwordx4 v[220:221], off
	s_mov_b32 m0, s50
	s_nop 0
	global_load_lds_dwordx4 v[222:223], off
	s_waitcnt vmcnt(8)
	s_waitcnt lgkmcnt(0)
	s_barrier
	s_setprio 1
	s_waitcnt lgkmcnt(0)
	v_mfma_f32_16x16x32_bf16 v[62:65], v[152:155], v[184:187], v[62:65]
	v_mfma_f32_16x16x32_bf16 v[58:61], v[160:163], v[184:187], v[58:61]
	v_mfma_f32_16x16x32_bf16 v[54:57], v[152:155], v[192:195], v[54:57]
	v_mfma_f32_16x16x32_bf16 v[50:53], v[160:163], v[192:195], v[50:53]
	v_mfma_f32_16x16x32_bf16 v[30:33], v[152:155], v[200:203], v[30:33]
	v_mfma_f32_16x16x32_bf16 v[26:29], v[160:163], v[200:203], v[26:29]
	v_mfma_f32_16x16x32_bf16 v[22:25], v[152:155], v[208:211], v[22:25]
	v_mfma_f32_16x16x32_bf16 v[18:21], v[160:163], v[208:211], v[18:21]
	v_mfma_f32_16x16x32_bf16 v[62:65], v[156:159], v[188:191], v[62:65]
	v_mfma_f32_16x16x32_bf16 v[58:61], v[164:167], v[188:191], v[58:61]
	v_mfma_f32_16x16x32_bf16 v[54:57], v[156:159], v[196:199], v[54:57]
	v_mfma_f32_16x16x32_bf16 v[50:53], v[164:167], v[196:199], v[50:53]
	v_mfma_f32_16x16x32_bf16 v[30:33], v[156:159], v[204:207], v[30:33]
	v_mfma_f32_16x16x32_bf16 v[26:29], v[164:167], v[204:207], v[26:29]
	v_mfma_f32_16x16x32_bf16 v[22:25], v[156:159], v[212:215], v[22:25]
	v_mfma_f32_16x16x32_bf16 v[18:21], v[164:167], v[212:215], v[18:21]
	s_setprio 0
	s_setprio 1
	v_mfma_f32_16x16x32_bf16 v[46:49], v[168:171], v[184:187], v[46:49]
	v_mfma_f32_16x16x32_bf16 v[42:45], v[176:179], v[184:187], v[42:45]
	v_mfma_f32_16x16x32_bf16 v[38:41], v[168:171], v[192:195], v[38:41]
	v_mfma_f32_16x16x32_bf16 v[34:37], v[176:179], v[192:195], v[34:37]
	v_mfma_f32_16x16x32_bf16 v[14:17], v[168:171], v[200:203], v[14:17]
	v_mfma_f32_16x16x32_bf16 v[10:13], v[176:179], v[200:203], v[10:13]
	v_mfma_f32_16x16x32_bf16 v[6:9], v[168:171], v[208:211], v[6:9]
	v_mfma_f32_16x16x32_bf16 v[2:5], v[176:179], v[208:211], v[2:5]
	v_mfma_f32_16x16x32_bf16 v[46:49], v[172:175], v[188:191], v[46:49]
	v_mfma_f32_16x16x32_bf16 v[42:45], v[180:183], v[188:191], v[42:45]
	v_mfma_f32_16x16x32_bf16 v[38:41], v[172:175], v[196:199], v[38:41]
	v_mfma_f32_16x16x32_bf16 v[34:37], v[180:183], v[196:199], v[34:37]
	s_setprio 2
	s_barrier
	v_mfma_f32_16x16x32_bf16 v[14:17], v[172:175], v[204:207], v[14:17]
	v_mfma_f32_16x16x32_bf16 v[10:13], v[180:183], v[204:207], v[10:13]
	v_mfma_f32_16x16x32_bf16 v[6:9], v[172:175], v[212:215], v[6:9]
	v_mfma_f32_16x16x32_bf16 v[2:5], v[180:183], v[212:215], v[2:5]
	s_setprio 0
	s_add_i32 s68, 0, 0x18000
	s_add_i32 s69, 0, 0x1c000
	v_add_u32_e32 v164, s68, v150
	v_add_u32_e32 v180, s69, v150
	ds_read_b128 v[152:155], v164
	ds_read_b128 v[156:159], v164 offset:1024
	ds_read_b128 v[160:163], v164 offset:2048
	ds_read_b128 v[164:167], v164 offset:3072
	ds_read_b128 v[168:171], v180
	ds_read_b128 v[172:175], v180 offset:1024
	ds_read_b128 v[176:179], v180 offset:2048
	ds_read_b128 v[180:183], v180 offset:3072
	s_add_u32 s36, s36, 0x80000
	s_addc_u32 s37, s37, 0
	s_mov_b32 m0, s51
	v_lshl_add_u64 v[224:225], s[36:37], 0, v[130:131]
	ds_read_b128 v[184:187], v151 offset:32768
	ds_read_b128 v[188:191], v151 offset:33792
	ds_read_b128 v[192:195], v151 offset:34816
	ds_read_b128 v[196:199], v151 offset:35840
	ds_read_b128 v[200:203], v151 offset:36864
	ds_read_b128 v[204:207], v151 offset:37888
	ds_read_b128 v[208:211], v151 offset:38912
	ds_read_b128 v[212:215], v151 offset:39936
	global_load_lds_dwordx4 v[224:225], off
	v_lshl_add_u64 v[224:225], s[36:37], 0, v[134:135]
	s_mov_b32 m0, s57
	s_nop 0
	global_load_lds_dwordx4 v[224:225], off
	s_waitcnt vmcnt(8)
	s_waitcnt lgkmcnt(0)
	s_barrier
	s_setprio 1
	s_waitcnt lgkmcnt(0)
	v_mfma_f32_16x16x32_bf16 v[126:129], v[152:155], v[184:187], v[126:129]
	v_mfma_f32_16x16x32_bf16 v[122:125], v[160:163], v[184:187], v[122:125]
	v_mfma_f32_16x16x32_bf16 v[118:121], v[152:155], v[192:195], v[118:121]
	v_mfma_f32_16x16x32_bf16 v[114:117], v[160:163], v[192:195], v[114:117]
	v_mfma_f32_16x16x32_bf16 v[94:97], v[152:155], v[200:203], v[94:97]
	v_mfma_f32_16x16x32_bf16 v[90:93], v[160:163], v[200:203], v[90:93]
	v_mfma_f32_16x16x32_bf16 v[86:89], v[152:155], v[208:211], v[86:89]
	v_mfma_f32_16x16x32_bf16 v[82:85], v[160:163], v[208:211], v[82:85]
	v_mfma_f32_16x16x32_bf16 v[126:129], v[156:159], v[188:191], v[126:129]
	v_mfma_f32_16x16x32_bf16 v[122:125], v[164:167], v[188:191], v[122:125]
	v_mfma_f32_16x16x32_bf16 v[118:121], v[156:159], v[196:199], v[118:121]
	v_mfma_f32_16x16x32_bf16 v[114:117], v[164:167], v[196:199], v[114:117]
	v_mfma_f32_16x16x32_bf16 v[94:97], v[156:159], v[204:207], v[94:97]
	v_mfma_f32_16x16x32_bf16 v[90:93], v[164:167], v[204:207], v[90:93]
	v_mfma_f32_16x16x32_bf16 v[86:89], v[156:159], v[212:215], v[86:89]
	v_mfma_f32_16x16x32_bf16 v[82:85], v[164:167], v[212:215], v[82:85]
	s_setprio 0
	s_setprio 1
	v_mfma_f32_16x16x32_bf16 v[110:113], v[168:171], v[184:187], v[110:113]
	v_mfma_f32_16x16x32_bf16 v[106:109], v[176:179], v[184:187], v[106:109]
	v_mfma_f32_16x16x32_bf16 v[102:105], v[168:171], v[192:195], v[102:105]
	v_mfma_f32_16x16x32_bf16 v[98:101], v[176:179], v[192:195], v[98:101]
	v_mfma_f32_16x16x32_bf16 v[78:81], v[168:171], v[200:203], v[78:81]
	v_mfma_f32_16x16x32_bf16 v[74:77], v[176:179], v[200:203], v[74:77]
	v_mfma_f32_16x16x32_bf16 v[70:73], v[168:171], v[208:211], v[70:73]
	v_mfma_f32_16x16x32_bf16 v[66:69], v[176:179], v[208:211], v[66:69]
	v_mfma_f32_16x16x32_bf16 v[110:113], v[172:175], v[188:191], v[110:113]
	v_mfma_f32_16x16x32_bf16 v[106:109], v[180:183], v[188:191], v[106:109]
	v_mfma_f32_16x16x32_bf16 v[102:105], v[172:175], v[196:199], v[102:105]
	v_mfma_f32_16x16x32_bf16 v[98:101], v[180:183], v[196:199], v[98:101]
	s_setprio 2
	s_barrier
	v_mfma_f32_16x16x32_bf16 v[78:81], v[172:175], v[204:207], v[78:81]
	v_mfma_f32_16x16x32_bf16 v[74:77], v[180:183], v[204:207], v[74:77]
	v_mfma_f32_16x16x32_bf16 v[70:73], v[172:175], v[212:215], v[70:73]
	v_mfma_f32_16x16x32_bf16 v[66:69], v[180:183], v[212:215], v[66:69]
	s_setprio 0
	s_add_i32 s36, s68, s48
	v_lshl_add_u64 v[216:217], v[216:217], 0, s[18:19]
	s_mov_b32 m0, s36
	ds_read_b128 v[184:187], v151 offset:49152
	ds_read_b128 v[188:191], v151 offset:50176
	ds_read_b128 v[192:195], v151 offset:51200
	ds_read_b128 v[196:199], v151 offset:52224
	ds_read_b128 v[200:203], v151 offset:53248
	ds_read_b128 v[204:207], v151 offset:54272
	ds_read_b128 v[208:211], v151 offset:55296
	ds_read_b128 v[212:215], v151 offset:56320
	global_load_lds_dwordx4 v[216:217], off
	s_add_i32 m0, s36, 0x2000
	s_add_u32 s34, s34, 0x80080
	v_lshl_add_u64 v[216:217], v[218:219], 0, s[18:19]
	s_addc_u32 s35, s35, 0
	s_add_i32 s36, s69, s48
	global_load_lds_dwordx4 v[216:217], off
	v_lshl_add_u64 v[216:217], s[34:35], 0, v[132:133]
	s_mov_b32 m0, s36
	s_nop 0
	global_load_lds_dwordx4 v[216:217], off
	v_lshl_add_u64 v[216:217], s[34:35], 0, v[136:137]
	s_add_i32 m0, s36, 0x2000
	s_nop 0
	global_load_lds_dwordx4 v[216:217], off
	v_lshl_add_u64 v[216:217], v[220:221], 0, s[18:19]
	s_mov_b32 m0, s60
	s_nop 0
	global_load_lds_dwordx4 v[216:217], off
	v_lshl_add_u64 v[216:217], v[222:223], 0, s[18:19]
	s_mov_b32 m0, s61
	s_nop 0
	global_load_lds_dwordx4 v[216:217], off
	s_waitcnt vmcnt(8)
	s_waitcnt lgkmcnt(0)
	s_barrier
	s_setprio 1
	s_waitcnt lgkmcnt(0)
	v_mfma_f32_16x16x32_bf16 v[62:65], v[152:155], v[184:187], v[62:65]
	v_mfma_f32_16x16x32_bf16 v[58:61], v[160:163], v[184:187], v[58:61]
	v_mfma_f32_16x16x32_bf16 v[54:57], v[152:155], v[192:195], v[54:57]
	v_mfma_f32_16x16x32_bf16 v[50:53], v[160:163], v[192:195], v[50:53]
	v_mfma_f32_16x16x32_bf16 v[30:33], v[152:155], v[200:203], v[30:33]
	v_mfma_f32_16x16x32_bf16 v[26:29], v[160:163], v[200:203], v[26:29]
	v_mfma_f32_16x16x32_bf16 v[22:25], v[152:155], v[208:211], v[22:25]
	v_mfma_f32_16x16x32_bf16 v[18:21], v[160:163], v[208:211], v[18:21]
	v_mfma_f32_16x16x32_bf16 v[62:65], v[156:159], v[188:191], v[62:65]
	v_mfma_f32_16x16x32_bf16 v[58:61], v[164:167], v[188:191], v[58:61]
	v_mfma_f32_16x16x32_bf16 v[54:57], v[156:159], v[196:199], v[54:57]
	v_mfma_f32_16x16x32_bf16 v[50:53], v[164:167], v[196:199], v[50:53]
	v_mfma_f32_16x16x32_bf16 v[30:33], v[156:159], v[204:207], v[30:33]
	v_mfma_f32_16x16x32_bf16 v[26:29], v[164:167], v[204:207], v[26:29]
	v_mfma_f32_16x16x32_bf16 v[22:25], v[156:159], v[212:215], v[22:25]
	v_mfma_f32_16x16x32_bf16 v[18:21], v[164:167], v[212:215], v[18:21]
	s_setprio 0
	s_setprio 1
	v_mfma_f32_16x16x32_bf16 v[46:49], v[168:171], v[184:187], v[46:49]
	v_mfma_f32_16x16x32_bf16 v[42:45], v[176:179], v[184:187], v[42:45]
	v_mfma_f32_16x16x32_bf16 v[38:41], v[168:171], v[192:195], v[38:41]
	v_mfma_f32_16x16x32_bf16 v[34:37], v[176:179], v[192:195], v[34:37]
	v_mfma_f32_16x16x32_bf16 v[14:17], v[168:171], v[200:203], v[14:17]
	v_mfma_f32_16x16x32_bf16 v[10:13], v[176:179], v[200:203], v[10:13]
	v_mfma_f32_16x16x32_bf16 v[6:9], v[168:171], v[208:211], v[6:9]
	v_mfma_f32_16x16x32_bf16 v[2:5], v[176:179], v[208:211], v[2:5]
	v_mfma_f32_16x16x32_bf16 v[46:49], v[172:175], v[188:191], v[46:49]
	v_mfma_f32_16x16x32_bf16 v[42:45], v[180:183], v[188:191], v[42:45]
	v_mfma_f32_16x16x32_bf16 v[38:41], v[172:175], v[196:199], v[38:41]
	v_mfma_f32_16x16x32_bf16 v[34:37], v[180:183], v[196:199], v[34:37]
	s_setprio 2
	s_barrier
	v_mfma_f32_16x16x32_bf16 v[14:17], v[172:175], v[204:207], v[14:17]
	v_mfma_f32_16x16x32_bf16 v[10:13], v[180:183], v[204:207], v[10:13]
	v_mfma_f32_16x16x32_bf16 v[6:9], v[172:175], v[212:215], v[6:9]
	v_mfma_f32_16x16x32_bf16 v[2:5], v[180:183], v[212:215], v[2:5]
	s_setprio 0
	s_add_i32 s67, s67, 2
	s_add_u32 s26, s26, 0x100
	s_addc_u32 s27, s27, 0
	s_cmp_gt_u32 s67, 29
	s_cbranch_scc0 .LBB0_761
	s_add_u32 s26, s21, 0xffffff00
	s_addc_u32 s27, s66, -1
	s_andn2_b64 vcc, exec, s[6:7]
	s_cbranch_vccnz .LBB0_753
	v_mov_b32_e32 v2, 0
	s_mov_b32 s8, s64
	s_mov_b32 s14, s20
	s_mov_b64 s[26:27], s[24:25]
	s_mov_b64 s[16:17], s[22:23]
	s_mov_b32 s59, s65
	v_mov_b32_e32 v3, v2
	v_mov_b32_e32 v4, v2
	v_mov_b32_e32 v5, v2
	v_mov_b32_e32 v6, v2
	v_mov_b32_e32 v7, v2
	v_mov_b32_e32 v8, v2
	v_mov_b32_e32 v9, v2
	v_mov_b32_e32 v10, v2
	v_mov_b32_e32 v11, v2
	v_mov_b32_e32 v12, v2
	v_mov_b32_e32 v13, v2
	v_mov_b32_e32 v14, v2
	v_mov_b32_e32 v15, v2
	v_mov_b32_e32 v16, v2
	v_mov_b32_e32 v17, v2
	v_mov_b32_e32 v34, v2
	v_mov_b32_e32 v35, v2
	v_mov_b32_e32 v36, v2
	v_mov_b32_e32 v37, v2
	v_mov_b32_e32 v38, v2
	v_mov_b32_e32 v39, v2
	v_mov_b32_e32 v40, v2
	v_mov_b32_e32 v41, v2
	v_mov_b32_e32 v42, v2
	v_mov_b32_e32 v43, v2
	v_mov_b32_e32 v44, v2
	v_mov_b32_e32 v45, v2
	v_mov_b32_e32 v46, v2
	v_mov_b32_e32 v47, v2
	v_mov_b32_e32 v48, v2
	v_mov_b32_e32 v49, v2
	v_mov_b32_e32 v18, v2
	v_mov_b32_e32 v19, v2
	v_mov_b32_e32 v20, v2
	v_mov_b32_e32 v21, v2
	v_mov_b32_e32 v22, v2
	v_mov_b32_e32 v23, v2
	v_mov_b32_e32 v24, v2
	v_mov_b32_e32 v25, v2
	v_mov_b32_e32 v26, v2
	v_mov_b32_e32 v27, v2
	v_mov_b32_e32 v28, v2
	v_mov_b32_e32 v29, v2
	v_mov_b32_e32 v30, v2
	v_mov_b32_e32 v31, v2
	v_mov_b32_e32 v32, v2
	v_mov_b32_e32 v33, v2
	v_mov_b32_e32 v50, v2
	v_mov_b32_e32 v51, v2
	v_mov_b32_e32 v52, v2
	v_mov_b32_e32 v53, v2
	v_mov_b32_e32 v54, v2
	v_mov_b32_e32 v55, v2
	v_mov_b32_e32 v56, v2
	v_mov_b32_e32 v57, v2
	v_mov_b32_e32 v58, v2
	v_mov_b32_e32 v59, v2
	v_mov_b32_e32 v60, v2
	v_mov_b32_e32 v61, v2
	v_mov_b32_e32 v62, v2
	v_mov_b32_e32 v63, v2
	v_mov_b32_e32 v64, v2
	v_mov_b32_e32 v65, v2
	v_mov_b32_e32 v66, v2
	v_mov_b32_e32 v67, v2
	v_mov_b32_e32 v68, v2
	v_mov_b32_e32 v69, v2
	v_mov_b32_e32 v70, v2
	v_mov_b32_e32 v71, v2
	v_mov_b32_e32 v72, v2
	v_mov_b32_e32 v73, v2
	v_mov_b32_e32 v74, v2
	v_mov_b32_e32 v75, v2
	v_mov_b32_e32 v76, v2
	v_mov_b32_e32 v77, v2
	v_mov_b32_e32 v78, v2
	v_mov_b32_e32 v79, v2
	v_mov_b32_e32 v80, v2
	v_mov_b32_e32 v81, v2
	v_mov_b32_e32 v98, v2
	v_mov_b32_e32 v99, v2
	v_mov_b32_e32 v100, v2
	v_mov_b32_e32 v101, v2
	v_mov_b32_e32 v102, v2
	v_mov_b32_e32 v103, v2
	v_mov_b32_e32 v104, v2
	v_mov_b32_e32 v105, v2
	v_mov_b32_e32 v106, v2
	v_mov_b32_e32 v107, v2
	v_mov_b32_e32 v108, v2
	v_mov_b32_e32 v109, v2
	v_mov_b32_e32 v110, v2
	v_mov_b32_e32 v111, v2
	v_mov_b32_e32 v112, v2
	v_mov_b32_e32 v113, v2
	v_mov_b32_e32 v82, v2
	v_mov_b32_e32 v83, v2
	v_mov_b32_e32 v84, v2
	v_mov_b32_e32 v85, v2
	v_mov_b32_e32 v86, v2
	v_mov_b32_e32 v87, v2
	v_mov_b32_e32 v88, v2
	v_mov_b32_e32 v89, v2
	v_mov_b32_e32 v90, v2
	v_mov_b32_e32 v91, v2
	v_mov_b32_e32 v92, v2
	v_mov_b32_e32 v93, v2
	v_mov_b32_e32 v94, v2
	v_mov_b32_e32 v95, v2
	v_mov_b32_e32 v96, v2
	v_mov_b32_e32 v97, v2
	v_mov_b32_e32 v114, v2
	v_mov_b32_e32 v115, v2
	v_mov_b32_e32 v116, v2
	v_mov_b32_e32 v117, v2
	v_mov_b32_e32 v118, v2
	v_mov_b32_e32 v119, v2
	v_mov_b32_e32 v120, v2
	v_mov_b32_e32 v121, v2
	v_mov_b32_e32 v122, v2
	v_mov_b32_e32 v123, v2
	v_mov_b32_e32 v124, v2
	v_mov_b32_e32 v125, v2
	v_mov_b32_e32 v126, v2
	v_mov_b32_e32 v127, v2
	v_mov_b32_e32 v128, v2
	v_mov_b32_e32 v129, v2
	s_branch .LBB0_753

.LBB0_965:
	s_cmp_eq_u32 s89, 12
	s_cselect_b64 s[14:15], -1, 0
	s_and_b64 s[14:15], s[14:15], exec
	s_cselect_b32 s15, s54, s88
	s_cselect_b32 s14, s55, s87
	s_add_u32 s90, s12, 0xfffc0080
	s_addc_u32 s91, s13, -1
	s_cmp_eq_u32 s89, 12
	s_cselect_b64 s[42:43], -1, 0
	s_and_b64 s[40:41], s[42:43], exec
	s_cselect_b32 s40, s51, s90
	s_cselect_b32 s41, s50, s91
	s_and_b64 vcc, s[38:39], s[42:43]
	s_and_b64 s[42:43], vcc, exec
	s_cselect_b32 s63, s56, s63
	s_cselect_b32 s64, s86, s64
	s_add_i32 s42, 0, 0x10000
	v_add_u32_e32 v147, s42, v194
	s_add_i32 s43, 0, 0x14000
	ds_read_b128 v[130:133], v147
	ds_read_b128 v[134:137], v147 offset:1024
	ds_read_b128 v[148:151], v147 offset:2048
	ds_read_b128 v[152:155], v147 offset:3072
	v_add_u32_e32 v147, s43, v194
	ds_read_b128 v[156:159], v147
	ds_read_b128 v[160:163], v147 offset:1024
	ds_read_b128 v[164:167], v147 offset:2048
	ds_read_b128 v[168:171], v147 offset:3072
	v_cndmask_b32_e32 v146, v146, v129, vcc
	v_cndmask_b32_e32 v138, v138, v128, vcc
	v_lshl_add_u64 v[228:229], s[12:13], 0, v[144:145]
	s_add_i32 m0, s62, 0xc000
	ds_read_b128 v[196:199], v195
	ds_read_b128 v[200:203], v195 offset:1024
	ds_read_b128 v[204:207], v195 offset:2048
	ds_read_b128 v[208:211], v195 offset:3072
	ds_read_b128 v[212:215], v195 offset:4096
	ds_read_b128 v[216:219], v195 offset:5120
	ds_read_b128 v[220:223], v195 offset:6144
	ds_read_b128 v[224:227], v195 offset:7168
	global_load_lds_dwordx4 v[228:229], off
	v_lshl_add_u64 v[228:229], s[12:13], 0, v[142:143]
	s_add_i32 m0, s62, 0xe000
	s_nop 0
	global_load_lds_dwordx4 v[228:229], off
	s_waitcnt vmcnt(8)
	s_waitcnt lgkmcnt(0)
	s_barrier
	s_setprio 1
	s_waitcnt lgkmcnt(0)
	v_mfma_f32_16x16x32_bf16 v[124:127], v[130:133], v[196:199], v[124:127]
	v_mfma_f32_16x16x32_bf16 v[120:123], v[148:151], v[196:199], v[120:123]
	v_mfma_f32_16x16x32_bf16 v[108:111], v[130:133], v[204:207], v[108:111]
	v_mfma_f32_16x16x32_bf16 v[104:107], v[148:151], v[204:207], v[104:107]
	v_mfma_f32_16x16x32_bf16 v[92:95], v[130:133], v[212:215], v[92:95]
	v_mfma_f32_16x16x32_bf16 v[88:91], v[148:151], v[212:215], v[88:91]
	v_mfma_f32_16x16x32_bf16 v[76:79], v[130:133], v[220:223], v[76:79]
	v_mfma_f32_16x16x32_bf16 v[72:75], v[148:151], v[220:223], v[72:75]
	v_mfma_f32_16x16x32_bf16 v[124:127], v[134:137], v[200:203], v[124:127]
	v_mfma_f32_16x16x32_bf16 v[120:123], v[152:155], v[200:203], v[120:123]
	v_mfma_f32_16x16x32_bf16 v[108:111], v[134:137], v[208:211], v[108:111]
	v_mfma_f32_16x16x32_bf16 v[104:107], v[152:155], v[208:211], v[104:107]
	v_mfma_f32_16x16x32_bf16 v[92:95], v[134:137], v[216:219], v[92:95]
	v_mfma_f32_16x16x32_bf16 v[88:91], v[152:155], v[216:219], v[88:91]
	v_mfma_f32_16x16x32_bf16 v[76:79], v[134:137], v[224:227], v[76:79]
	v_mfma_f32_16x16x32_bf16 v[72:75], v[152:155], v[224:227], v[72:75]
	s_setprio 0
	s_setprio 1
	v_mfma_f32_16x16x32_bf16 v[116:119], v[156:159], v[196:199], v[116:119]
	v_mfma_f32_16x16x32_bf16 v[112:115], v[164:167], v[196:199], v[112:115]
	v_mfma_f32_16x16x32_bf16 v[100:103], v[156:159], v[204:207], v[100:103]
	v_mfma_f32_16x16x32_bf16 v[96:99], v[164:167], v[204:207], v[96:99]
	v_mfma_f32_16x16x32_bf16 v[84:87], v[156:159], v[212:215], v[84:87]
	v_mfma_f32_16x16x32_bf16 v[80:83], v[164:167], v[212:215], v[80:83]
	v_mfma_f32_16x16x32_bf16 v[68:71], v[156:159], v[220:223], v[68:71]
	v_mfma_f32_16x16x32_bf16 v[64:67], v[164:167], v[220:223], v[64:67]
	v_mfma_f32_16x16x32_bf16 v[116:119], v[160:163], v[200:203], v[116:119]
	v_mfma_f32_16x16x32_bf16 v[112:115], v[168:171], v[200:203], v[112:115]
	v_mfma_f32_16x16x32_bf16 v[100:103], v[160:163], v[208:211], v[100:103]
	v_mfma_f32_16x16x32_bf16 v[96:99], v[168:171], v[208:211], v[96:99]
	s_setprio 2
	s_barrier
	v_mfma_f32_16x16x32_bf16 v[84:87], v[160:163], v[216:219], v[84:87]
	v_mfma_f32_16x16x32_bf16 v[80:83], v[168:171], v[216:219], v[80:83]
	v_mfma_f32_16x16x32_bf16 v[68:71], v[160:163], v[224:227], v[68:71]
	v_mfma_f32_16x16x32_bf16 v[64:67], v[168:171], v[224:227], v[64:67]
	s_setprio 0
	s_add_i32 s42, s42, s49
	s_mov_b32 m0, s42
	ds_read_b128 v[196:199], v195 offset:16384
	ds_read_b128 v[200:203], v195 offset:17408
	ds_read_b128 v[204:207], v195 offset:18432
	ds_read_b128 v[208:211], v195 offset:19456
	ds_read_b128 v[212:215], v195 offset:20480
	ds_read_b128 v[216:219], v195 offset:21504
	ds_read_b128 v[220:223], v195 offset:22528
	ds_read_b128 v[224:227], v195 offset:23552
	global_load_lds_dwordx4 v138, s[14:15]
	v_mov_b32_e32 v147, v139
	s_add_i32 m0, s42, 0x2000
	v_lshl_add_u64 v[228:229], s[14:15], 0, v[138:139]
	v_lshl_add_u64 v[230:231], s[14:15], 0, v[146:147]
	global_load_lds_dwordx4 v146, s[14:15]
	s_add_u32 s14, s14, s64
	s_addc_u32 s15, s15, s63
	s_add_i32 s42, s43, s49
	s_mov_b32 m0, s42
	v_lshl_add_u64 v[236:237], s[40:41], 0, v[144:145]
	global_load_lds_dwordx4 v138, s[14:15]
	s_add_i32 m0, s42, 0x2000
	v_lshl_add_u64 v[238:239], s[40:41], 0, v[142:143]
	global_load_lds_dwordx4 v146, s[14:15]
	s_mov_b32 m0, s62
	v_lshl_add_u64 v[232:233], s[14:15], 0, v[138:139]
	global_load_lds_dwordx4 v[236:237], off
	s_mov_b32 m0, s65
	v_lshl_add_u64 v[234:235], s[14:15], 0, v[146:147]
	global_load_lds_dwordx4 v[238:239], off
	s_waitcnt vmcnt(8)
	s_waitcnt lgkmcnt(0)
	s_barrier
	s_setprio 1
	s_waitcnt lgkmcnt(0)
	v_mfma_f32_16x16x32_bf16 v[60:63], v[130:133], v[196:199], v[60:63]
	v_mfma_f32_16x16x32_bf16 v[56:59], v[148:151], v[196:199], v[56:59]
	v_mfma_f32_16x16x32_bf16 v[44:47], v[130:133], v[204:207], v[44:47]
	v_mfma_f32_16x16x32_bf16 v[40:43], v[148:151], v[204:207], v[40:43]
	v_mfma_f32_16x16x32_bf16 v[28:31], v[130:133], v[212:215], v[28:31]
	v_mfma_f32_16x16x32_bf16 v[24:27], v[148:151], v[212:215], v[24:27]
	v_mfma_f32_16x16x32_bf16 v[12:15], v[130:133], v[220:223], v[12:15]
	v_mfma_f32_16x16x32_bf16 v[8:11], v[148:151], v[220:223], v[8:11]
	v_mfma_f32_16x16x32_bf16 v[60:63], v[134:137], v[200:203], v[60:63]
	v_mfma_f32_16x16x32_bf16 v[56:59], v[152:155], v[200:203], v[56:59]
	v_mfma_f32_16x16x32_bf16 v[44:47], v[134:137], v[208:211], v[44:47]
	v_mfma_f32_16x16x32_bf16 v[40:43], v[152:155], v[208:211], v[40:43]
	v_mfma_f32_16x16x32_bf16 v[28:31], v[134:137], v[216:219], v[28:31]
	v_mfma_f32_16x16x32_bf16 v[24:27], v[152:155], v[216:219], v[24:27]
	v_mfma_f32_16x16x32_bf16 v[12:15], v[134:137], v[224:227], v[12:15]
	v_mfma_f32_16x16x32_bf16 v[8:11], v[152:155], v[224:227], v[8:11]
	s_setprio 0
	s_setprio 1
	v_mfma_f32_16x16x32_bf16 v[52:55], v[156:159], v[196:199], v[52:55]
	v_mfma_f32_16x16x32_bf16 v[48:51], v[164:167], v[196:199], v[48:51]
	v_mfma_f32_16x16x32_bf16 v[36:39], v[156:159], v[204:207], v[36:39]
	v_mfma_f32_16x16x32_bf16 v[32:35], v[164:167], v[204:207], v[32:35]
	v_mfma_f32_16x16x32_bf16 v[20:23], v[156:159], v[212:215], v[20:23]
	v_mfma_f32_16x16x32_bf16 v[16:19], v[164:167], v[212:215], v[16:19]
	v_mfma_f32_16x16x32_bf16 v[4:7], v[156:159], v[220:223], v[4:7]
	v_mfma_f32_16x16x32_bf16 v[0:3], v[164:167], v[220:223], v[0:3]
	v_mfma_f32_16x16x32_bf16 v[52:55], v[160:163], v[200:203], v[52:55]
	v_mfma_f32_16x16x32_bf16 v[48:51], v[168:171], v[200:203], v[48:51]
	v_mfma_f32_16x16x32_bf16 v[36:39], v[160:163], v[208:211], v[36:39]
	v_mfma_f32_16x16x32_bf16 v[32:35], v[168:171], v[208:211], v[32:35]
	s_setprio 2
	s_barrier
	v_mfma_f32_16x16x32_bf16 v[20:23], v[160:163], v[216:219], v[20:23]
	v_mfma_f32_16x16x32_bf16 v[16:19], v[168:171], v[216:219], v[16:19]
	v_mfma_f32_16x16x32_bf16 v[4:7], v[160:163], v[224:227], v[4:7]
	v_mfma_f32_16x16x32_bf16 v[0:3], v[168:171], v[224:227], v[0:3]
	s_setprio 0
	s_add_i32 s42, 0, 0x18000
	v_add_u32_e32 v147, s42, v194
	s_add_i32 s43, 0, 0x1c000
	ds_read_b128 v[130:133], v147
	ds_read_b128 v[134:137], v147 offset:1024
	ds_read_b128 v[148:151], v147 offset:2048
	ds_read_b128 v[152:155], v147 offset:3072
	v_add_u32_e32 v147, s43, v194
	ds_read_b128 v[156:159], v147
	ds_read_b128 v[160:163], v147 offset:1024
	ds_read_b128 v[164:167], v147 offset:2048
	ds_read_b128 v[168:171], v147 offset:3072
	s_add_u32 s14, s40, 0x40000
	s_addc_u32 s15, s41, 0
	s_mov_b32 m0, s66
	v_lshl_add_u64 v[240:241], s[14:15], 0, v[144:145]
	ds_read_b128 v[196:199], v195 offset:32768
	ds_read_b128 v[200:203], v195 offset:33792
	ds_read_b128 v[204:207], v195 offset:34816
	ds_read_b128 v[208:211], v195 offset:35840
	ds_read_b128 v[212:215], v195 offset:36864
	ds_read_b128 v[216:219], v195 offset:37888
	ds_read_b128 v[220:223], v195 offset:38912
	ds_read_b128 v[224:227], v195 offset:39936
	global_load_lds_dwordx4 v[240:241], off
	v_lshl_add_u64 v[240:241], s[14:15], 0, v[142:143]
	s_mov_b32 m0, s67
	s_nop 0
	global_load_lds_dwordx4 v[240:241], off
	s_waitcnt vmcnt(8)
	s_waitcnt lgkmcnt(0)
	s_barrier
	s_setprio 1
	s_waitcnt lgkmcnt(0)
	v_mfma_f32_16x16x32_bf16 v[124:127], v[130:133], v[196:199], v[124:127]
	v_mfma_f32_16x16x32_bf16 v[120:123], v[148:151], v[196:199], v[120:123]
	v_mfma_f32_16x16x32_bf16 v[108:111], v[130:133], v[204:207], v[108:111]
	v_mfma_f32_16x16x32_bf16 v[104:107], v[148:151], v[204:207], v[104:107]
	v_mfma_f32_16x16x32_bf16 v[92:95], v[130:133], v[212:215], v[92:95]
	v_mfma_f32_16x16x32_bf16 v[88:91], v[148:151], v[212:215], v[88:91]
	v_mfma_f32_16x16x32_bf16 v[76:79], v[130:133], v[220:223], v[76:79]
	v_mfma_f32_16x16x32_bf16 v[72:75], v[148:151], v[220:223], v[72:75]
	v_mfma_f32_16x16x32_bf16 v[124:127], v[134:137], v[200:203], v[124:127]
	v_mfma_f32_16x16x32_bf16 v[120:123], v[152:155], v[200:203], v[120:123]
	v_mfma_f32_16x16x32_bf16 v[108:111], v[134:137], v[208:211], v[108:111]
	v_mfma_f32_16x16x32_bf16 v[104:107], v[152:155], v[208:211], v[104:107]
	v_mfma_f32_16x16x32_bf16 v[92:95], v[134:137], v[216:219], v[92:95]
	v_mfma_f32_16x16x32_bf16 v[88:91], v[152:155], v[216:219], v[88:91]
	v_mfma_f32_16x16x32_bf16 v[76:79], v[134:137], v[224:227], v[76:79]
	v_mfma_f32_16x16x32_bf16 v[72:75], v[152:155], v[224:227], v[72:75]
	s_setprio 0
	s_setprio 1
	v_mfma_f32_16x16x32_bf16 v[116:119], v[156:159], v[196:199], v[116:119]
	v_mfma_f32_16x16x32_bf16 v[112:115], v[164:167], v[196:199], v[112:115]
	v_mfma_f32_16x16x32_bf16 v[100:103], v[156:159], v[204:207], v[100:103]
	v_mfma_f32_16x16x32_bf16 v[96:99], v[164:167], v[204:207], v[96:99]
	v_mfma_f32_16x16x32_bf16 v[84:87], v[156:159], v[212:215], v[84:87]
	v_mfma_f32_16x16x32_bf16 v[80:83], v[164:167], v[212:215], v[80:83]
	v_mfma_f32_16x16x32_bf16 v[68:71], v[156:159], v[220:223], v[68:71]
	v_mfma_f32_16x16x32_bf16 v[64:67], v[164:167], v[220:223], v[64:67]
	v_mfma_f32_16x16x32_bf16 v[116:119], v[160:163], v[200:203], v[116:119]
	v_mfma_f32_16x16x32_bf16 v[112:115], v[168:171], v[200:203], v[112:115]
	v_mfma_f32_16x16x32_bf16 v[100:103], v[160:163], v[208:211], v[100:103]
	v_mfma_f32_16x16x32_bf16 v[96:99], v[168:171], v[208:211], v[96:99]
	s_setprio 2
	s_barrier
	v_mfma_f32_16x16x32_bf16 v[84:87], v[160:163], v[216:219], v[84:87]
	v_mfma_f32_16x16x32_bf16 v[80:83], v[168:171], v[216:219], v[80:83]
	v_mfma_f32_16x16x32_bf16 v[68:71], v[160:163], v[224:227], v[68:71]
	v_mfma_f32_16x16x32_bf16 v[64:67], v[168:171], v[224:227], v[64:67]
	s_setprio 0
	s_add_i32 s14, s42, s49
	v_lshl_add_u64 v[228:229], v[228:229], 0, s[16:17]
	s_mov_b32 m0, s14
	ds_read_b128 v[196:199], v195 offset:49152
	ds_read_b128 v[200:203], v195 offset:50176
	ds_read_b128 v[204:207], v195 offset:51200
	ds_read_b128 v[208:211], v195 offset:52224
	ds_read_b128 v[212:215], v195 offset:53248
	ds_read_b128 v[216:219], v195 offset:54272
	ds_read_b128 v[220:223], v195 offset:55296
	ds_read_b128 v[224:227], v195 offset:56320
	global_load_lds_dwordx4 v[228:229], off
	v_lshl_add_u64 v[228:229], v[230:231], 0, s[16:17]
	s_add_i32 m0, s14, 0x2000
	s_add_i32 s14, s43, s49
	global_load_lds_dwordx4 v[228:229], off
	v_lshl_add_u64 v[228:229], v[232:233], 0, s[16:17]
	s_mov_b32 m0, s14
	s_nop 0
	global_load_lds_dwordx4 v[228:229], off
	v_lshl_add_u64 v[228:229], v[234:235], 0, s[16:17]
	s_add_i32 m0, s14, 0x2000
	s_nop 0
	global_load_lds_dwordx4 v[228:229], off
	v_lshl_add_u64 v[228:229], v[236:237], 0, s[16:17]
	s_mov_b32 m0, s72
	s_nop 0
	global_load_lds_dwordx4 v[228:229], off
	v_lshl_add_u64 v[228:229], v[238:239], 0, s[16:17]
	s_mov_b32 m0, s73
	s_nop 0
	global_load_lds_dwordx4 v[228:229], off
	s_waitcnt vmcnt(8)
	s_waitcnt lgkmcnt(0)
	s_barrier
	s_setprio 1
	s_waitcnt lgkmcnt(0)
	v_mfma_f32_16x16x32_bf16 v[60:63], v[130:133], v[196:199], v[60:63]
	v_mfma_f32_16x16x32_bf16 v[56:59], v[148:151], v[196:199], v[56:59]
	v_mfma_f32_16x16x32_bf16 v[44:47], v[130:133], v[204:207], v[44:47]
	v_mfma_f32_16x16x32_bf16 v[40:43], v[148:151], v[204:207], v[40:43]
	v_mfma_f32_16x16x32_bf16 v[28:31], v[130:133], v[212:215], v[28:31]
	v_mfma_f32_16x16x32_bf16 v[24:27], v[148:151], v[212:215], v[24:27]
	v_mfma_f32_16x16x32_bf16 v[12:15], v[130:133], v[220:223], v[12:15]
	v_mfma_f32_16x16x32_bf16 v[8:11], v[148:151], v[220:223], v[8:11]
	v_mfma_f32_16x16x32_bf16 v[60:63], v[134:137], v[200:203], v[60:63]
	v_mfma_f32_16x16x32_bf16 v[56:59], v[152:155], v[200:203], v[56:59]
	v_mfma_f32_16x16x32_bf16 v[44:47], v[134:137], v[208:211], v[44:47]
	v_mfma_f32_16x16x32_bf16 v[40:43], v[152:155], v[208:211], v[40:43]
	v_mfma_f32_16x16x32_bf16 v[28:31], v[134:137], v[216:219], v[28:31]
	v_mfma_f32_16x16x32_bf16 v[24:27], v[152:155], v[216:219], v[24:27]
	v_mfma_f32_16x16x32_bf16 v[12:15], v[134:137], v[224:227], v[12:15]
	v_mfma_f32_16x16x32_bf16 v[8:11], v[152:155], v[224:227], v[8:11]
	s_setprio 0
	s_setprio 1
	v_mfma_f32_16x16x32_bf16 v[52:55], v[156:159], v[196:199], v[52:55]
	v_mfma_f32_16x16x32_bf16 v[48:51], v[164:167], v[196:199], v[48:51]
	v_mfma_f32_16x16x32_bf16 v[36:39], v[156:159], v[204:207], v[36:39]
	v_mfma_f32_16x16x32_bf16 v[32:35], v[164:167], v[204:207], v[32:35]
	v_mfma_f32_16x16x32_bf16 v[20:23], v[156:159], v[212:215], v[20:23]
	v_mfma_f32_16x16x32_bf16 v[16:19], v[164:167], v[212:215], v[16:19]
	v_mfma_f32_16x16x32_bf16 v[4:7], v[156:159], v[220:223], v[4:7]
	v_mfma_f32_16x16x32_bf16 v[0:3], v[164:167], v[220:223], v[0:3]
	v_mfma_f32_16x16x32_bf16 v[52:55], v[160:163], v[200:203], v[52:55]
	v_mfma_f32_16x16x32_bf16 v[48:51], v[168:171], v[200:203], v[48:51]
	v_mfma_f32_16x16x32_bf16 v[36:39], v[160:163], v[208:211], v[36:39]
	v_mfma_f32_16x16x32_bf16 v[32:35], v[168:171], v[208:211], v[32:35]
	s_setprio 2
	s_barrier
	v_mfma_f32_16x16x32_bf16 v[20:23], v[160:163], v[216:219], v[20:23]
	v_mfma_f32_16x16x32_bf16 v[16:19], v[168:171], v[216:219], v[16:19]
	v_mfma_f32_16x16x32_bf16 v[4:7], v[160:163], v[224:227], v[4:7]
	v_mfma_f32_16x16x32_bf16 v[0:3], v[168:171], v[224:227], v[0:3]
	s_setprio 0
	s_add_i32 s89, s89, 2
	s_add_u32 s12, s12, 0x100
	s_addc_u32 s13, s13, 0
	s_add_u32 s87, s87, 0x100
	s_addc_u32 s88, s88, 0
	s_cmp_gt_u32 s89, 13
	s_cbranch_scc0 .LBB0_965
	s_and_b64 vcc, exec, s[26:27]
	s_cbranch_vccz .LBB0_968
	s_barrier

.LBB0_1511:
	v_add_u32_e32 v162, s50, v148
	v_add_u32_e32 v178, s51, v148
	s_add_u32 s34, s16, s26
	ds_read_b128 v[150:153], v162
	ds_read_b128 v[154:157], v162 offset:1024
	ds_read_b128 v[158:161], v162 offset:2048
	ds_read_b128 v[162:165], v162 offset:3072
	ds_read_b128 v[166:169], v178
	ds_read_b128 v[170:173], v178 offset:1024
	ds_read_b128 v[174:177], v178 offset:2048
	ds_read_b128 v[178:181], v178 offset:3072
	s_addc_u32 s35, s17, s27
	s_add_u32 s34, s34, 0x100
	s_addc_u32 s35, s35, 0
	s_add_u32 s57, s21, s26
	s_addc_u32 s58, s55, s27
	s_cmpk_eq_i32 s26, 0xf00
	s_cselect_b32 s37, s29, s35
	s_cselect_b32 s36, s28, s34
	s_cselect_b32 s35, s31, s58
	s_cselect_b32 s34, s30, s57
	v_lshl_add_u64 v[214:215], v[144:145], 0, s[26:27]
	s_add_i32 m0, s13, 0xc000
	ds_read_b128 v[182:185], v149
	ds_read_b128 v[186:189], v149 offset:1024
	ds_read_b128 v[190:193], v149 offset:2048
	ds_read_b128 v[194:197], v149 offset:3072
	ds_read_b128 v[198:201], v149 offset:4096
	ds_read_b128 v[202:205], v149 offset:5120
	ds_read_b128 v[206:209], v149 offset:6144
	ds_read_b128 v[210:213], v149 offset:7168
	global_load_lds_dwordx4 v[214:215], off
	v_lshl_add_u64 v[214:215], v[146:147], 0, s[26:27]
	s_add_i32 m0, s13, 0xe000
	s_nop 0
	global_load_lds_dwordx4 v[214:215], off
	s_waitcnt vmcnt(8)
	s_waitcnt lgkmcnt(0)
	s_barrier
	s_setprio 1
	s_waitcnt lgkmcnt(0)
	v_mfma_f32_16x16x32_bf16 v[128:131], v[150:153], v[182:185], v[128:131]
	v_mfma_f32_16x16x32_bf16 v[124:127], v[158:161], v[182:185], v[124:127]
	v_mfma_f32_16x16x32_bf16 v[116:119], v[150:153], v[190:193], v[116:119]
	v_mfma_f32_16x16x32_bf16 v[108:111], v[158:161], v[190:193], v[108:111]
	v_mfma_f32_16x16x32_bf16 v[100:103], v[150:153], v[198:201], v[100:103]
	v_mfma_f32_16x16x32_bf16 v[92:95], v[158:161], v[198:201], v[92:95]
	v_mfma_f32_16x16x32_bf16 v[84:87], v[150:153], v[206:209], v[84:87]
	v_mfma_f32_16x16x32_bf16 v[76:79], v[158:161], v[206:209], v[76:79]
	v_mfma_f32_16x16x32_bf16 v[128:131], v[154:157], v[186:189], v[128:131]
	v_mfma_f32_16x16x32_bf16 v[124:127], v[162:165], v[186:189], v[124:127]
	v_mfma_f32_16x16x32_bf16 v[116:119], v[154:157], v[194:197], v[116:119]
	v_mfma_f32_16x16x32_bf16 v[108:111], v[162:165], v[194:197], v[108:111]
	v_mfma_f32_16x16x32_bf16 v[100:103], v[154:157], v[202:205], v[100:103]
	v_mfma_f32_16x16x32_bf16 v[92:95], v[162:165], v[202:205], v[92:95]
	v_mfma_f32_16x16x32_bf16 v[84:87], v[154:157], v[210:213], v[84:87]
	v_mfma_f32_16x16x32_bf16 v[76:79], v[162:165], v[210:213], v[76:79]
	s_setprio 0
	s_setprio 1
	v_mfma_f32_16x16x32_bf16 v[120:123], v[166:169], v[182:185], v[120:123]
	v_mfma_f32_16x16x32_bf16 v[112:115], v[174:177], v[182:185], v[112:115]
	v_mfma_f32_16x16x32_bf16 v[104:107], v[166:169], v[190:193], v[104:107]
	v_mfma_f32_16x16x32_bf16 v[96:99], v[174:177], v[190:193], v[96:99]
	v_mfma_f32_16x16x32_bf16 v[88:91], v[166:169], v[198:201], v[88:91]
	v_mfma_f32_16x16x32_bf16 v[80:83], v[174:177], v[198:201], v[80:83]
	v_mfma_f32_16x16x32_bf16 v[72:75], v[166:169], v[206:209], v[72:75]
	v_mfma_f32_16x16x32_bf16 v[68:71], v[174:177], v[206:209], v[68:71]
	v_mfma_f32_16x16x32_bf16 v[120:123], v[170:173], v[186:189], v[120:123]
	v_mfma_f32_16x16x32_bf16 v[112:115], v[178:181], v[186:189], v[112:115]
	v_mfma_f32_16x16x32_bf16 v[104:107], v[170:173], v[194:197], v[104:107]
	v_mfma_f32_16x16x32_bf16 v[96:99], v[178:181], v[194:197], v[96:99]
	s_setprio 2
	s_barrier
	v_mfma_f32_16x16x32_bf16 v[88:91], v[170:173], v[202:205], v[88:91]
	v_mfma_f32_16x16x32_bf16 v[80:83], v[178:181], v[202:205], v[80:83]
	v_mfma_f32_16x16x32_bf16 v[72:75], v[170:173], v[210:213], v[72:75]
	v_mfma_f32_16x16x32_bf16 v[68:71], v[178:181], v[210:213], v[68:71]
	s_setprio 0
	s_add_i32 s57, s50, s42
	v_lshl_add_u64 v[214:215], s[34:35], 0, v[2:3]
	s_mov_b32 m0, s57
	ds_read_b128 v[182:185], v149 offset:16384
	ds_read_b128 v[186:189], v149 offset:17408
	ds_read_b128 v[190:193], v149 offset:18432
	ds_read_b128 v[194:197], v149 offset:19456
	ds_read_b128 v[198:201], v149 offset:20480
	ds_read_b128 v[202:205], v149 offset:21504
	ds_read_b128 v[206:209], v149 offset:22528
	ds_read_b128 v[210:213], v149 offset:23552
	global_load_lds_dwordx4 v[214:215], off
	s_add_i32 m0, s57, 0x2000
	s_add_u32 s58, s34, 0x80000
	v_lshl_add_u64 v[216:217], s[34:35], 0, v[134:135]
	s_addc_u32 s59, s35, 0
	s_add_i32 s57, s51, s42
	global_load_lds_dwordx4 v[216:217], off
	v_lshl_add_u64 v[218:219], s[58:59], 0, v[2:3]
	s_mov_b32 m0, s57
	v_lshl_add_u64 v[220:221], s[36:37], 0, v[132:133]
	global_load_lds_dwordx4 v[218:219], off
	v_lshl_add_u64 v[218:219], s[58:59], 0, v[134:135]
	s_add_i32 m0, s57, 0x2000
	s_nop 0
	global_load_lds_dwordx4 v[218:219], off
	v_lshl_add_u64 v[218:219], s[36:37], 0, v[0:1]
	s_mov_b32 m0, s13
	s_nop 0
	global_load_lds_dwordx4 v[218:219], off
	s_mov_b32 m0, s43
	s_nop 0
	global_load_lds_dwordx4 v[220:221], off
	s_waitcnt vmcnt(8)
	s_waitcnt lgkmcnt(0)
	s_barrier
	s_setprio 1
	s_waitcnt lgkmcnt(0)
	v_mfma_f32_16x16x32_bf16 v[64:67], v[150:153], v[182:185], v[64:67]
	v_mfma_f32_16x16x32_bf16 v[60:63], v[158:161], v[182:185], v[60:63]
	v_mfma_f32_16x16x32_bf16 v[52:55], v[150:153], v[190:193], v[52:55]
	v_mfma_f32_16x16x32_bf16 v[44:47], v[158:161], v[190:193], v[44:47]
	v_mfma_f32_16x16x32_bf16 v[36:39], v[150:153], v[198:201], v[36:39]
	v_mfma_f32_16x16x32_bf16 v[28:31], v[158:161], v[198:201], v[28:31]
	v_mfma_f32_16x16x32_bf16 v[20:23], v[150:153], v[206:209], v[20:23]
	v_mfma_f32_16x16x32_bf16 v[12:15], v[158:161], v[206:209], v[12:15]
	v_mfma_f32_16x16x32_bf16 v[64:67], v[154:157], v[186:189], v[64:67]
	v_mfma_f32_16x16x32_bf16 v[60:63], v[162:165], v[186:189], v[60:63]
	v_mfma_f32_16x16x32_bf16 v[52:55], v[154:157], v[194:197], v[52:55]
	v_mfma_f32_16x16x32_bf16 v[44:47], v[162:165], v[194:197], v[44:47]
	v_mfma_f32_16x16x32_bf16 v[36:39], v[154:157], v[202:205], v[36:39]
	v_mfma_f32_16x16x32_bf16 v[28:31], v[162:165], v[202:205], v[28:31]
	v_mfma_f32_16x16x32_bf16 v[20:23], v[154:157], v[210:213], v[20:23]
	v_mfma_f32_16x16x32_bf16 v[12:15], v[162:165], v[210:213], v[12:15]
	s_setprio 0
	s_setprio 1
	v_mfma_f32_16x16x32_bf16 v[56:59], v[166:169], v[182:185], v[56:59]
	v_mfma_f32_16x16x32_bf16 v[48:51], v[174:177], v[182:185], v[48:51]
	v_mfma_f32_16x16x32_bf16 v[40:43], v[166:169], v[190:193], v[40:43]
	v_mfma_f32_16x16x32_bf16 v[32:35], v[174:177], v[190:193], v[32:35]
	v_mfma_f32_16x16x32_bf16 v[24:27], v[166:169], v[198:201], v[24:27]
	v_mfma_f32_16x16x32_bf16 v[16:19], v[174:177], v[198:201], v[16:19]
	v_mfma_f32_16x16x32_bf16 v[8:11], v[166:169], v[206:209], v[8:11]
	v_mfma_f32_16x16x32_bf16 v[4:7], v[174:177], v[206:209], v[4:7]
	v_mfma_f32_16x16x32_bf16 v[56:59], v[170:173], v[186:189], v[56:59]
	v_mfma_f32_16x16x32_bf16 v[48:51], v[178:181], v[186:189], v[48:51]
	v_mfma_f32_16x16x32_bf16 v[40:43], v[170:173], v[194:197], v[40:43]
	v_mfma_f32_16x16x32_bf16 v[32:35], v[178:181], v[194:197], v[32:35]
	s_setprio 2
	s_barrier
	v_mfma_f32_16x16x32_bf16 v[24:27], v[170:173], v[202:205], v[24:27]
	v_mfma_f32_16x16x32_bf16 v[16:19], v[178:181], v[202:205], v[16:19]
	v_mfma_f32_16x16x32_bf16 v[8:11], v[170:173], v[210:213], v[8:11]
	v_mfma_f32_16x16x32_bf16 v[4:7], v[178:181], v[210:213], v[4:7]
	s_setprio 0
	s_add_i32 s57, 0, 0x18000
	s_add_i32 s58, 0, 0x1c000
	v_add_u32_e32 v162, s57, v148
	v_add_u32_e32 v178, s58, v148
	ds_read_b128 v[150:153], v162
	ds_read_b128 v[154:157], v162 offset:1024
	ds_read_b128 v[158:161], v162 offset:2048
	ds_read_b128 v[162:165], v162 offset:3072
	ds_read_b128 v[166:169], v178
	ds_read_b128 v[170:173], v178 offset:1024
	ds_read_b128 v[174:177], v178 offset:2048
	ds_read_b128 v[178:181], v178 offset:3072
	s_add_u32 s36, s36, 0x80000
	s_addc_u32 s37, s37, 0
	s_mov_b32 m0, s45
	v_lshl_add_u64 v[222:223], s[36:37], 0, v[0:1]
	ds_read_b128 v[182:185], v149 offset:32768
	ds_read_b128 v[186:189], v149 offset:33792
	ds_read_b128 v[190:193], v149 offset:34816
	ds_read_b128 v[194:197], v149 offset:35840
	ds_read_b128 v[198:201], v149 offset:36864
	ds_read_b128 v[202:205], v149 offset:37888
	ds_read_b128 v[206:209], v149 offset:38912
	ds_read_b128 v[210:213], v149 offset:39936
	global_load_lds_dwordx4 v[222:223], off
	v_lshl_add_u64 v[222:223], s[36:37], 0, v[132:133]
	s_mov_b32 m0, s46
	s_nop 0
	global_load_lds_dwordx4 v[222:223], off
	s_waitcnt vmcnt(8)
	s_waitcnt lgkmcnt(0)
	s_barrier
	s_setprio 1
	s_waitcnt lgkmcnt(0)
	v_mfma_f32_16x16x32_bf16 v[128:131], v[150:153], v[182:185], v[128:131]
	v_mfma_f32_16x16x32_bf16 v[124:127], v[158:161], v[182:185], v[124:127]
	v_mfma_f32_16x16x32_bf16 v[116:119], v[150:153], v[190:193], v[116:119]
	v_mfma_f32_16x16x32_bf16 v[108:111], v[158:161], v[190:193], v[108:111]
	v_mfma_f32_16x16x32_bf16 v[100:103], v[150:153], v[198:201], v[100:103]
	v_mfma_f32_16x16x32_bf16 v[92:95], v[158:161], v[198:201], v[92:95]
	v_mfma_f32_16x16x32_bf16 v[84:87], v[150:153], v[206:209], v[84:87]
	v_mfma_f32_16x16x32_bf16 v[76:79], v[158:161], v[206:209], v[76:79]
	v_mfma_f32_16x16x32_bf16 v[128:131], v[154:157], v[186:189], v[128:131]
	v_mfma_f32_16x16x32_bf16 v[124:127], v[162:165], v[186:189], v[124:127]
	v_mfma_f32_16x16x32_bf16 v[116:119], v[154:157], v[194:197], v[116:119]
	v_mfma_f32_16x16x32_bf16 v[108:111], v[162:165], v[194:197], v[108:111]
	v_mfma_f32_16x16x32_bf16 v[100:103], v[154:157], v[202:205], v[100:103]
	v_mfma_f32_16x16x32_bf16 v[92:95], v[162:165], v[202:205], v[92:95]
	v_mfma_f32_16x16x32_bf16 v[84:87], v[154:157], v[210:213], v[84:87]
	v_mfma_f32_16x16x32_bf16 v[76:79], v[162:165], v[210:213], v[76:79]
	s_setprio 0
	s_setprio 1
	v_mfma_f32_16x16x32_bf16 v[120:123], v[166:169], v[182:185], v[120:123]
	v_mfma_f32_16x16x32_bf16 v[112:115], v[174:177], v[182:185], v[112:115]
	v_mfma_f32_16x16x32_bf16 v[104:107], v[166:169], v[190:193], v[104:107]
	v_mfma_f32_16x16x32_bf16 v[96:99], v[174:177], v[190:193], v[96:99]
	v_mfma_f32_16x16x32_bf16 v[88:91], v[166:169], v[198:201], v[88:91]
	v_mfma_f32_16x16x32_bf16 v[80:83], v[174:177], v[198:201], v[80:83]
	v_mfma_f32_16x16x32_bf16 v[72:75], v[166:169], v[206:209], v[72:75]
	v_mfma_f32_16x16x32_bf16 v[68:71], v[174:177], v[206:209], v[68:71]
	v_mfma_f32_16x16x32_bf16 v[120:123], v[170:173], v[186:189], v[120:123]
	v_mfma_f32_16x16x32_bf16 v[112:115], v[178:181], v[186:189], v[112:115]
	v_mfma_f32_16x16x32_bf16 v[104:107], v[170:173], v[194:197], v[104:107]
	v_mfma_f32_16x16x32_bf16 v[96:99], v[178:181], v[194:197], v[96:99]
	s_setprio 2
	s_barrier
	v_mfma_f32_16x16x32_bf16 v[88:91], v[170:173], v[202:205], v[88:91]
	v_mfma_f32_16x16x32_bf16 v[80:83], v[178:181], v[202:205], v[80:83]
	v_mfma_f32_16x16x32_bf16 v[72:75], v[170:173], v[210:213], v[72:75]
	v_mfma_f32_16x16x32_bf16 v[68:71], v[178:181], v[210:213], v[68:71]
	s_setprio 0
	s_add_i32 s36, s57, s42
	v_lshl_add_u64 v[214:215], v[214:215], 0, s[18:19]
	s_mov_b32 m0, s36
	ds_read_b128 v[182:185], v149 offset:49152
	ds_read_b128 v[186:189], v149 offset:50176
	ds_read_b128 v[190:193], v149 offset:51200
	ds_read_b128 v[194:197], v149 offset:52224
	ds_read_b128 v[198:201], v149 offset:53248
	ds_read_b128 v[202:205], v149 offset:54272
	ds_read_b128 v[206:209], v149 offset:55296
	ds_read_b128 v[210:213], v149 offset:56320
	global_load_lds_dwordx4 v[214:215], off
	s_add_i32 m0, s36, 0x2000
	s_add_u32 s34, s34, 0x80080
	v_lshl_add_u64 v[214:215], v[216:217], 0, s[18:19]
	s_addc_u32 s35, s35, 0
	s_add_i32 s36, s58, s42
	global_load_lds_dwordx4 v[214:215], off
	v_lshl_add_u64 v[214:215], s[34:35], 0, v[2:3]
	s_mov_b32 m0, s36
	s_nop 0
	global_load_lds_dwordx4 v[214:215], off
	v_lshl_add_u64 v[214:215], s[34:35], 0, v[134:135]
	s_add_i32 m0, s36, 0x2000
	s_nop 0
	global_load_lds_dwordx4 v[214:215], off
	v_lshl_add_u64 v[214:215], v[218:219], 0, s[18:19]
	s_mov_b32 m0, s48
	s_nop 0
	global_load_lds_dwordx4 v[214:215], off
	v_lshl_add_u64 v[214:215], v[220:221], 0, s[18:19]
	s_mov_b32 m0, s49
	s_nop 0
	global_load_lds_dwordx4 v[214:215], off
	s_waitcnt vmcnt(8)
	s_waitcnt lgkmcnt(0)
	s_barrier
	s_setprio 1
	s_waitcnt lgkmcnt(0)
	v_mfma_f32_16x16x32_bf16 v[64:67], v[150:153], v[182:185], v[64:67]
	v_mfma_f32_16x16x32_bf16 v[60:63], v[158:161], v[182:185], v[60:63]
	v_mfma_f32_16x16x32_bf16 v[52:55], v[150:153], v[190:193], v[52:55]
	v_mfma_f32_16x16x32_bf16 v[44:47], v[158:161], v[190:193], v[44:47]
	v_mfma_f32_16x16x32_bf16 v[36:39], v[150:153], v[198:201], v[36:39]
	v_mfma_f32_16x16x32_bf16 v[28:31], v[158:161], v[198:201], v[28:31]
	v_mfma_f32_16x16x32_bf16 v[20:23], v[150:153], v[206:209], v[20:23]
	v_mfma_f32_16x16x32_bf16 v[12:15], v[158:161], v[206:209], v[12:15]
	v_mfma_f32_16x16x32_bf16 v[64:67], v[154:157], v[186:189], v[64:67]
	v_mfma_f32_16x16x32_bf16 v[60:63], v[162:165], v[186:189], v[60:63]
	v_mfma_f32_16x16x32_bf16 v[52:55], v[154:157], v[194:197], v[52:55]
	v_mfma_f32_16x16x32_bf16 v[44:47], v[162:165], v[194:197], v[44:47]
	v_mfma_f32_16x16x32_bf16 v[36:39], v[154:157], v[202:205], v[36:39]
	v_mfma_f32_16x16x32_bf16 v[28:31], v[162:165], v[202:205], v[28:31]
	v_mfma_f32_16x16x32_bf16 v[20:23], v[154:157], v[210:213], v[20:23]
	v_mfma_f32_16x16x32_bf16 v[12:15], v[162:165], v[210:213], v[12:15]
	s_setprio 0
	s_setprio 1
	v_mfma_f32_16x16x32_bf16 v[56:59], v[166:169], v[182:185], v[56:59]
	v_mfma_f32_16x16x32_bf16 v[48:51], v[174:177], v[182:185], v[48:51]
	v_mfma_f32_16x16x32_bf16 v[40:43], v[166:169], v[190:193], v[40:43]
	v_mfma_f32_16x16x32_bf16 v[32:35], v[174:177], v[190:193], v[32:35]
	v_mfma_f32_16x16x32_bf16 v[24:27], v[166:169], v[198:201], v[24:27]
	v_mfma_f32_16x16x32_bf16 v[16:19], v[174:177], v[198:201], v[16:19]
	v_mfma_f32_16x16x32_bf16 v[8:11], v[166:169], v[206:209], v[8:11]
	v_mfma_f32_16x16x32_bf16 v[4:7], v[174:177], v[206:209], v[4:7]
	v_mfma_f32_16x16x32_bf16 v[56:59], v[170:173], v[186:189], v[56:59]
	v_mfma_f32_16x16x32_bf16 v[48:51], v[178:181], v[186:189], v[48:51]
	v_mfma_f32_16x16x32_bf16 v[40:43], v[170:173], v[194:197], v[40:43]
	v_mfma_f32_16x16x32_bf16 v[32:35], v[178:181], v[194:197], v[32:35]
	s_setprio 2
	s_barrier
	v_mfma_f32_16x16x32_bf16 v[24:27], v[170:173], v[202:205], v[24:27]
	v_mfma_f32_16x16x32_bf16 v[16:19], v[178:181], v[202:205], v[16:19]
	v_mfma_f32_16x16x32_bf16 v[8:11], v[170:173], v[210:213], v[8:11]
	v_mfma_f32_16x16x32_bf16 v[4:7], v[178:181], v[210:213], v[4:7]
	s_setprio 0
	s_add_i32 s56, s56, 2
	s_add_u32 s26, s26, 0x100
	s_addc_u32 s27, s27, 0
	s_cmp_gt_u32 s56, 29
	s_cbranch_scc0 .LBB0_1511
	s_add_u32 s26, s21, 0xffffff00
	s_addc_u32 s27, s55, -1
	s_andn2_b64 vcc, exec, s[4:5]
	s_cbranch_vccnz .LBB0_1503
	v_mov_b32_e32 v4, 0
	s_mov_b32 s14, s53
	s_mov_b32 s12, s20
	s_mov_b64 s[26:27], s[24:25]
	s_mov_b64 s[16:17], s[22:23]
	s_mov_b32 s47, s54
	v_mov_b32_e32 v5, v4
	v_mov_b32_e32 v6, v4
	v_mov_b32_e32 v7, v4
	v_mov_b32_e32 v8, v4
	v_mov_b32_e32 v9, v4
	v_mov_b32_e32 v10, v4
	v_mov_b32_e32 v11, v4
	v_mov_b32_e32 v16, v4
	v_mov_b32_e32 v17, v4
	v_mov_b32_e32 v18, v4
	v_mov_b32_e32 v19, v4
	v_mov_b32_e32 v24, v4
	v_mov_b32_e32 v25, v4
	v_mov_b32_e32 v26, v4
	v_mov_b32_e32 v27, v4
	v_mov_b32_e32 v32, v4
	v_mov_b32_e32 v33, v4
	v_mov_b32_e32 v34, v4
	v_mov_b32_e32 v35, v4
	v_mov_b32_e32 v40, v4
	v_mov_b32_e32 v41, v4
	v_mov_b32_e32 v42, v4
	v_mov_b32_e32 v43, v4
	v_mov_b32_e32 v48, v4
	v_mov_b32_e32 v49, v4
	v_mov_b32_e32 v50, v4
	v_mov_b32_e32 v51, v4
	v_mov_b32_e32 v56, v4
	v_mov_b32_e32 v57, v4
	v_mov_b32_e32 v58, v4
	v_mov_b32_e32 v59, v4
	v_mov_b32_e32 v12, v4
	v_mov_b32_e32 v13, v4
	v_mov_b32_e32 v14, v4
	v_mov_b32_e32 v15, v4
	v_mov_b32_e32 v20, v4
	v_mov_b32_e32 v21, v4
	v_mov_b32_e32 v22, v4
	v_mov_b32_e32 v23, v4
	v_mov_b32_e32 v28, v4
	v_mov_b32_e32 v29, v4
	v_mov_b32_e32 v30, v4
	v_mov_b32_e32 v31, v4
	v_mov_b32_e32 v36, v4
	v_mov_b32_e32 v37, v4
	v_mov_b32_e32 v38, v4
	v_mov_b32_e32 v39, v4
	v_mov_b32_e32 v44, v4
	v_mov_b32_e32 v45, v4
	v_mov_b32_e32 v46, v4
	v_mov_b32_e32 v47, v4
	v_mov_b32_e32 v52, v4
	v_mov_b32_e32 v53, v4
	v_mov_b32_e32 v54, v4
	v_mov_b32_e32 v55, v4
	v_mov_b32_e32 v60, v4
	v_mov_b32_e32 v61, v4
	v_mov_b32_e32 v62, v4
	v_mov_b32_e32 v63, v4
	v_mov_b32_e32 v64, v4
	v_mov_b32_e32 v65, v4
	v_mov_b32_e32 v66, v4
	v_mov_b32_e32 v67, v4
	v_mov_b32_e32 v68, v4
	v_mov_b32_e32 v69, v4
	v_mov_b32_e32 v70, v4
	v_mov_b32_e32 v71, v4
	v_mov_b32_e32 v72, v4
	v_mov_b32_e32 v73, v4
	v_mov_b32_e32 v74, v4
	v_mov_b32_e32 v75, v4
	v_mov_b32_e32 v80, v4
	v_mov_b32_e32 v81, v4
	v_mov_b32_e32 v82, v4
	v_mov_b32_e32 v83, v4
	v_mov_b32_e32 v88, v4
	v_mov_b32_e32 v89, v4
	v_mov_b32_e32 v90, v4
	v_mov_b32_e32 v91, v4
	v_mov_b32_e32 v96, v4
	v_mov_b32_e32 v97, v4
	v_mov_b32_e32 v98, v4
	v_mov_b32_e32 v99, v4
	v_mov_b32_e32 v104, v4
	v_mov_b32_e32 v105, v4
	v_mov_b32_e32 v106, v4
	v_mov_b32_e32 v107, v4
	v_mov_b32_e32 v112, v4
	v_mov_b32_e32 v113, v4
	v_mov_b32_e32 v114, v4
	v_mov_b32_e32 v115, v4
	v_mov_b32_e32 v120, v4
	v_mov_b32_e32 v121, v4
	v_mov_b32_e32 v122, v4
	v_mov_b32_e32 v123, v4
	v_mov_b32_e32 v76, v4
	v_mov_b32_e32 v77, v4
	v_mov_b32_e32 v78, v4
	v_mov_b32_e32 v79, v4
	v_mov_b32_e32 v84, v4
	v_mov_b32_e32 v85, v4
	v_mov_b32_e32 v86, v4
	v_mov_b32_e32 v87, v4
	v_mov_b32_e32 v92, v4
	v_mov_b32_e32 v93, v4
	v_mov_b32_e32 v94, v4
	v_mov_b32_e32 v95, v4
	v_mov_b32_e32 v100, v4
	v_mov_b32_e32 v101, v4
	v_mov_b32_e32 v102, v4
	v_mov_b32_e32 v103, v4
	v_mov_b32_e32 v108, v4
	v_mov_b32_e32 v109, v4
	v_mov_b32_e32 v110, v4
	v_mov_b32_e32 v111, v4
	v_mov_b32_e32 v116, v4
	v_mov_b32_e32 v117, v4
	v_mov_b32_e32 v118, v4
	v_mov_b32_e32 v119, v4
	v_mov_b32_e32 v124, v4
	v_mov_b32_e32 v125, v4
	v_mov_b32_e32 v126, v4
	v_mov_b32_e32 v127, v4
	v_mov_b32_e32 v128, v4
	v_mov_b32_e32 v129, v4
	v_mov_b32_e32 v130, v4
	v_mov_b32_e32 v131, v4
	s_branch .LBB0_1503
